# retention core: heavy waves issue next-chunk loads after score tile 3 instead of after their last tile
# baseline (speedup 1.0000x reference)
; #define LAS __attribute__((address_space(3)))
; __device__ __forceinline__ void ret_core_phase(const Frame& F0, const bf16_t* hp, const bf16_t* qp, bf16_t* ro) {
;     ...
;             if (lw < 4) RC_ISSUE();
;             unsigned pf = 0u;
;             if (w == 0) { const int n2 = (n + 2 < 32) ? n + 2 : 31, l = 64 * vs + lane, rr = (l & 511) >> 2, ln = l & 3;
;                 const char* pa_ = (l < 512) ? (const char*)kb + (size_t)(128 * n2 + rr) * RET_LD * 2 + ln * 128
;                                             : (const char*)qb + (size_t)n2 * (8 * 8 * 8192) + (size_t)((l - 512) >> 6) * (8 * 8192) + ((l - 512) & 63) * 128;
;                 pf = *(const unsigned*)pa_; }
;             f32x4 Pt[8];
; #pragma unroll
;             for (int jt = 0; jt < 8; ++jt) { Pt[jt] = (f32x4){0.f, 0.f, 0.f, 0.f};
;                 if (jt <= lw) {
;                     bf16x8 kf[8];
; #pragma unroll
;                     for (int ks = 0; ks < 8; ++ks) kf[ks] = *(const LAS bf16x8*)(F.lds + R_KS + (16 * jt + l15) * RK_STR + (32 * ks + 8 * g) * 2);
;                     __builtin_amdgcn_sched_barrier(0);
; #pragma unroll
;                     for (int ks = 0; ks < 8; ++ks) Pt[jt] = __builtin_amdgcn_mfma_f32_16x16x32_bf16(kf[ks], qc[ks], Pt[jt], 0, 0, 0);
;                     if (jt == lw) {
; #pragma unroll
;                         for (int r = 0; r < 4; ++r) if (4 * g + r > l15) Pt[jt][r] = 0.f; }
;                 } }
;             if (lw >= 4) RC_ISSUE();
.LBB0_799:
	s_andn2_b64 vcc, exec, s[8:9]
	s_cbranch_vccnz .Lmy_rc_skip
	s_cmp_eq_u32 s75, 0
	s_cbranch_scc1 .LBB0_814
	s_mov_b32 s67, s35
	s_lshl_b64 s[76:77], s[66:67], 13
	s_waitcnt vmcnt(14)
	v_lshl_add_u64 v[6:7], v[176:177], 0, s[76:77]
	global_store_dwordx2 v[6:7], v[156:157], off
	global_store_dwordx2 v[6:7], v[154:155], off offset:32
.LBB0_814:
	s_add_i32 s34, s75, 1
	s_cmpk_lg_i32 s66, 0xf00
	s_cselect_b32 s67, s34, 31
	s_mul_i32 s34, s67, 0x304000
	s_waitcnt vmcnt(10)
	v_lshl_add_u64 v[30:31], v[172:173], 0, s[34:35]
	v_add_co_u32_e32 v6, vcc, 0x60000, v30
	s_waitcnt vmcnt(8)
	v_lshl_add_u64 v[38:39], v[180:181], 0, s[34:35]
	v_addc_co_u32_e32 v7, vcc, 0, v31, vcc
	global_load_dwordx4 v[14:17], v[30:31], off
	global_load_dwordx4 v[18:21], v[6:7], off offset:2048
	v_add_co_u32_e32 v6, vcc, 0xc1000, v30
	s_lshl_b32 s34, s67, 19
	s_nop 0
	v_addc_co_u32_e32 v7, vcc, 0, v31, vcc
	v_add_co_u32_e32 v10, vcc, 0x121000, v30
	s_waitcnt vmcnt(6)
	v_lshl_add_u64 v[54:55], v[174:175], 0, s[34:35]
	v_addc_co_u32_e32 v11, vcc, 0, v31, vcc
	v_add_co_u32_e32 v22, vcc, 0x182000, v30
	global_load_dwordx4 v[6:9], v[6:7], off
	s_nop 0
	global_load_dwordx4 v[10:13], v[10:11], off offset:2048
	v_addc_co_u32_e32 v23, vcc, 0, v31, vcc
	v_add_co_u32_e32 v26, vcc, 0x1e2000, v30
	s_nop 1
	v_addc_co_u32_e32 v27, vcc, 0, v31, vcc
	v_add_co_u32_e32 v32, vcc, 0x243000, v30
	global_load_dwordx4 v[22:25], v[22:23], off
	s_nop 0
	global_load_dwordx4 v[26:29], v[26:27], off offset:2048
	v_addc_co_u32_e32 v33, vcc, 0, v31, vcc
	v_add_co_u32_e32 v34, vcc, 0x2a3000, v30
	s_nop 1
	v_addc_co_u32_e32 v35, vcc, 0, v31, vcc
	s_waitcnt vmcnt(6)
	v_add_co_u32_e32 v70, vcc, 0x1000, v54
	global_load_dwordx4 v[30:33], v[32:33], off
	s_nop 0
	global_load_dwordx4 v[34:37], v[34:35], off offset:2048
	v_addc_co_u32_e32 v71, vcc, 0, v55, vcc
	global_load_dwordx4 v[38:41], v[38:39], off
	s_nop 0
	global_load_dwordx4 v[42:45], v[54:55], off
	global_load_dwordx4 v[46:49], v[54:55], off offset:1024
	global_load_dwordx4 v[50:53], v[54:55], off offset:2048
	s_nop 0
	global_load_dwordx4 v[54:57], v[54:55], off offset:3072
	s_nop 0
	global_load_dwordx4 v[58:61], v[70:71], off
	global_load_dwordx4 v[62:65], v[70:71], off offset:1024
	global_load_dwordx4 v[66:69], v[70:71], off offset:2048
	s_nop 0
	global_load_dwordx4 v[70:73], v[70:71], off offset:3072
.Lmy_rc_skip:
	v_cndmask_b32_e64 v139, 0, 1, s[8:9]
	v_mov_b32_e32 v138, 0
	v_cmp_ne_u32_e64 s[50:51], 1, v139
	s_andn2_b64 vcc, exec, s[8:9]
	v_mov_b32_e32 v142, 0
	v_mov_b32_e32 v143, 0
	v_mov_b32_e32 v144, 0
	v_mov_b32_e32 v145, 0
	s_cbranch_vccnz .LBB0_802
	ds_read_b128 v[140:143], v191 offset:33792
	ds_read_b128 v[144:147], v191 offset:33856
	ds_read_b128 v[148:151], v191 offset:33920
	ds_read_b128 v[158:161], v191 offset:33984
	ds_read_b128 v[218:221], v191 offset:34048
	ds_read_b128 v[222:225], v191 offset:34112
	ds_read_b128 v[226:229], v191 offset:34176
	ds_read_b128 v[236:239], v191 offset:34240
	s_waitcnt lgkmcnt(7)
	v_mfma_f32_16x16x32_bf16 v[140:143], v[140:143], v[90:93], 0
	s_andn2_b64 vcc, exec, s[28:29]
	s_waitcnt lgkmcnt(6)
	v_mfma_f32_16x16x32_bf16 v[140:143], v[144:147], v[118:121], v[140:143]
	s_waitcnt lgkmcnt(5)
	v_mfma_f32_16x16x32_bf16 v[140:143], v[148:151], v[114:117], v[140:143]
	s_waitcnt lgkmcnt(4)
	v_mfma_f32_16x16x32_bf16 v[140:143], v[158:161], v[110:113], v[140:143]
	s_waitcnt lgkmcnt(3)
	v_mfma_f32_16x16x32_bf16 v[140:143], v[218:221], v[106:109], v[140:143]
	s_waitcnt lgkmcnt(2)
	v_mfma_f32_16x16x32_bf16 v[140:143], v[222:225], v[94:97], v[140:143]
	s_waitcnt lgkmcnt(1)
	v_mfma_f32_16x16x32_bf16 v[140:143], v[226:229], v[98:101], v[140:143]
	s_waitcnt lgkmcnt(0)
	v_mfma_f32_16x16x32_bf16 v[142:145], v[236:239], v[102:105], v[140:143]
	s_cbranch_vccnz .LBB0_802
	s_nop 4
	v_mov_b32_e32 v140, s35
	s_nop 0
	v_cndmask_b32_e64 v139, v142, v140, s[38:39]
	v_cndmask_b32_e64 v143, 0, v143, s[40:41]
	v_cndmask_b32_e64 v142, v139, v142, s[40:41]
	v_cndmask_b32_e64 v144, v144, 0, s[42:43]
	v_cndmask_b32_e64 v145, v145, 0, s[44:45]

; #define LAS __attribute__((address_space(3)))
; __device__ __forceinline__ void ret_core_phase(const Frame& F0, const bf16_t* hp, const bf16_t* qp, bf16_t* ro) {
;     ...
;             if (lw >= 4) RC_ISSUE();
;     ...
;             f32x4 O[2];
; #pragma unroll
;             for (int vt = 0; vt < 2; ++vt) { O[vt] = (f32x4){0.f, 0.f, 0.f, 0.f};
;                 bf16x8 sf[8];
; #pragma unroll
;                 for (int ks = 0; ks < 8; ++ks) sf[ks] = *(const LAS bf16x8*)(F.lds + R_ST + (16 * vt + l15) * RK_STR + (32 * ks + 8 * g) * 2);
;                 __builtin_amdgcn_sched_barrier(0);
; #pragma unroll
;                 for (int ks = 0; ks < 8; ++ks) O[vt] = __builtin_amdgcn_mfma_f32_16x16x32_bf16(sf[ks], qc[ks], O[vt], 0, 0, 0);
;                 __builtin_amdgcn_sched_barrier(0); }
;             bf16x8 vf[8];
;             ds_tr16_v(ldsb + R_VS + (4 * g + q) * RV_STR + 4 * p * 2, vf);
; #pragma unroll
;             for (int kk = 0; kk < 4; ++kk) {
;                 if (2 * kk <= lw) {
;                     const bf16x8 pf = pack8(Pt[2 * kk], Pt[2 * kk + 1]);
;                     O[0] = __builtin_amdgcn_mfma_f32_16x16x32_bf16(vf[2 * kk], pf, O[0], 0, 0, 0);
;                     O[1] = __builtin_amdgcn_mfma_f32_16x16x32_bf16(vf[2 * kk + 1], pf, O[1], 0, 0, 0);
.LBB0_811:
.LBB0_815:
	ds_read_b128 v[154:157], v216
	ds_read_b128 v[158:161], v216 offset:64
	ds_read_b128 v[218:221], v216 offset:128
	ds_read_b128 v[222:225], v216 offset:192
	ds_read_b128 v[226:229], v216 offset:256
	ds_read_b128 v[236:239], v216 offset:320
	ds_read_b128 v[240:243], v216 offset:384
	ds_read_b128 v[244:247], v216 offset:448
	s_waitcnt lgkmcnt(7)
	v_mfma_f32_16x16x32_bf16 v[154:157], v[154:157], v[90:93], 0
	s_waitcnt lgkmcnt(6)
	v_mfma_f32_16x16x32_bf16 v[154:157], v[158:161], v[118:121], v[154:157]
	s_waitcnt lgkmcnt(5)
	v_mfma_f32_16x16x32_bf16 v[154:157], v[218:221], v[114:117], v[154:157]
	s_waitcnt lgkmcnt(4)
	v_mfma_f32_16x16x32_bf16 v[154:157], v[222:225], v[110:113], v[154:157]
	s_waitcnt lgkmcnt(3)
	v_mfma_f32_16x16x32_bf16 v[154:157], v[226:229], v[106:109], v[154:157]
	s_waitcnt lgkmcnt(2)
	v_mfma_f32_16x16x32_bf16 v[154:157], v[236:239], v[94:97], v[154:157]
	s_waitcnt lgkmcnt(1)
	v_mfma_f32_16x16x32_bf16 v[154:157], v[240:243], v[98:101], v[154:157]
	s_waitcnt lgkmcnt(0)
	v_mfma_f32_16x16x32_bf16 v[154:157], v[244:247], v[102:105], v[154:157]
	ds_read_b128 v[158:161], v216 offset:8448
	ds_read_b128 v[218:221], v216 offset:8512
	ds_read_b128 v[222:225], v216 offset:8576
	ds_read_b128 v[226:229], v216 offset:8640
	ds_read_b128 v[236:239], v216 offset:8704
	ds_read_b128 v[240:243], v216 offset:8768
	ds_read_b128 v[244:247], v216 offset:8832
	ds_read_b128 v[248:251], v216 offset:8896
	s_waitcnt lgkmcnt(7)
	v_mfma_f32_16x16x32_bf16 v[90:93], v[158:161], v[90:93], 0
	s_waitcnt lgkmcnt(6)
	v_mfma_f32_16x16x32_bf16 v[90:93], v[218:221], v[118:121], v[90:93]
	s_waitcnt lgkmcnt(5)
	v_mfma_f32_16x16x32_bf16 v[90:93], v[222:225], v[114:117], v[90:93]
	s_waitcnt lgkmcnt(4)
	v_mfma_f32_16x16x32_bf16 v[90:93], v[226:229], v[110:113], v[90:93]
	s_waitcnt lgkmcnt(3)
	v_mfma_f32_16x16x32_bf16 v[90:93], v[236:239], v[106:109], v[90:93]
	s_waitcnt lgkmcnt(2)
	v_mfma_f32_16x16x32_bf16 v[90:93], v[240:243], v[94:97], v[90:93]
	s_waitcnt lgkmcnt(1)
	v_mfma_f32_16x16x32_bf16 v[90:93], v[244:247], v[98:101], v[90:93]
	s_waitcnt lgkmcnt(0)
	v_mfma_f32_16x16x32_bf16 v[158:161], v[248:251], v[102:105], v[90:93]
	ds_read_b64_tr_b16 v[118:119], v189 offset:0
	ds_read_b64_tr_b16 v[120:121], v189 offset:1280
	ds_read_b64_tr_b16 v[114:115], v189 offset:32
	ds_read_b64_tr_b16 v[116:117], v189 offset:1312
	ds_read_b64_tr_b16 v[110:111], v189 offset:2560
	ds_read_b64_tr_b16 v[112:113], v189 offset:3840
	ds_read_b64_tr_b16 v[106:107], v189 offset:2592
	ds_read_b64_tr_b16 v[108:109], v189 offset:3872
	ds_read_b64_tr_b16 v[102:103], v189 offset:5120
	ds_read_b64_tr_b16 v[104:105], v189 offset:6400
	ds_read_b64_tr_b16 v[98:99], v189 offset:5152
	ds_read_b64_tr_b16 v[100:101], v189 offset:6432
	ds_read_b64_tr_b16 v[94:95], v189 offset:7680
	ds_read_b64_tr_b16 v[96:97], v189 offset:8960
	ds_read_b64_tr_b16 v[90:91], v189 offset:7712
	ds_read_b64_tr_b16 v[92:93], v189 offset:8992
	s_waitcnt lgkmcnt(0)
	s_and_b64 vcc, exec, s[46:47]
	s_cbranch_vccnz .LBB0_821
	v_cvt_pk_bf16_f32 v126, v126, v127
	v_cvt_pk_bf16_f32 v127, v128, v129
	v_cvt_pk_bf16_f32 v128, v122, v123
	v_cvt_pk_bf16_f32 v129, v124, v125
	s_nop 1
	v_mfma_f32_16x16x32_bf16 v[154:157], v[118:121], v[126:129], v[154:157]
	v_mfma_f32_16x16x32_bf16 v[158:161], v[114:117], v[126:129], v[158:161]
	s_and_b64 vcc, exec, s[48:49]
	s_cbranch_vccz .LBB0_822
